# phase 15: skip the two block barriers for heads that reuse the staged K/V
# speedup vs baseline: 1.0202x; 1.0000x over previous
.Lp15_sk1:
	v_bfe_u32 v80, v85, 5, 1
	v_mad_i64_i32 v[0:1], s[4:5], v84, s40, v[82:83]
	s_lshl_b32 s16, s9, 7
	v_lshl_add_u64 v[0:1], v[0:1], 0, s[16:17]
	v_lshlrev_b32_e32 v86, 4, v80
	v_mov_b32_e32 v87, v81
	v_lshl_add_u64 v[114:115], v[0:1], 0, v[86:87]
	s_waitcnt lgkmcnt(0)
	s_cmp_lg_u32 s99, 0
	s_cbranch_scc1 .Lp15_nb1
	s_barrier
.Lp15_nb1:
	global_load_dwordx4 v[0:3], v[114:115], off
	global_load_dwordx4 v[102:105], v[114:115], off offset:32
	v_mad_u64_u32 v[92:93], s[4:5], v97, s50, v[86:87]
	ds_read_b128 v[4:7], v92
	ds_read_b128 v[8:11], v92 offset:32
	v_add_u32_e32 v95, 1, v124
	v_lshlrev_b32_e32 v126, 5, v95
	v_or_b32_e32 v12, v126, v96
	v_mad_u64_u32 v[118:119], s[4:5], v12, s50, v[86:87]
	v_add_u32_e32 v94, 2, v124
	v_lshlrev_b32_e32 v127, 5, v94
	v_or_b32_e32 v12, v127, v96
	v_mad_u64_u32 v[120:121], s[4:5], v12, s50, v[86:87]
	v_add_u32_e32 v93, 3, v124
	v_lshlrev_b32_e32 v128, 5, v93
	v_or_b32_e32 v16, v128, v96
	v_mad_u64_u32 v[122:123], s[4:5], v16, s50, v[86:87]
	s_lshl_b32 s4, s9, 2
	s_cmp_lg_u32 s6, 0
	s_cselect_b64 s[18:19], -1, 0
	s_add_i32 s53, s53, 1
	s_add_i32 s38, s38, 8
	s_and_b32 s99, s53, 7
	s_cbranch_scc1 .Lp15_same
	s_add_i32 s53, s53, s39
	s_lshl_b32 s99, s39, 3
	s_add_i32 s38, s38, s99

.LBB0_765:
	s_and_b32 s99, s53, 7
	s_cmp_eq_u32 s99, 0
	s_cselect_b64 s[100:101], -1, 0
	s_bfe_u32 s6, s53, 0x70004
	s_lshl_b32 s8, s6, 7
	v_mov_b32_e32 v85, v205
	s_add_i32 s10, s8, 0xffffff80
	v_and_b32_e32 v10, 7, v85
	v_ashrrev_i32_e32 v1, 3, v85
	s_lshl_b32 s4, s53, 3
	v_lshlrev_b32_e32 v2, 3, v10
	v_add_u32_e32 v11, s10, v1
	s_and_b32 s7, s38, 0xffffc000
	s_and_b32 s9, s4, 64
	v_cmp_lt_i32_e32 vcc, -1, v11
	v_mov_b32_e32 v0, 0
	v_lshlrev_b32_e32 v80, 1, v2
	v_mov_b32_e32 v6, 0
	v_mov_b32_e32 v7, 0
	v_mov_b32_e32 v8, 0
	v_mov_b32_e32 v9, 0
	v_mov_b32_e32 v2, 0
	v_mov_b32_e32 v3, 0
	v_mov_b32_e32 v4, 0
	v_mov_b32_e32 v5, 0
	s_cmp_lg_u32 s99, 0
	s_cbranch_scc1 .Lp15_nb0
	s_barrier
.Lp15_nb0:
	s_and_b64 vcc, vcc, s[100:101]
	s_and_saveexec_b64 s[4:5], vcc
	s_cbranch_execz .LBB0_767
	v_add_u32_e32 v4, s7, v11
	v_mov_b64_e32 v[2:3], s[44:45]
	v_mad_i64_i32 v[2:3], s[12:13], v4, s40, v[2:3]
	s_lshl_b32 s16, s9, 1
	v_lshl_add_u64 v[2:3], v[2:3], 0, s[16:17]
	v_lshl_add_u64 v[2:3], v[2:3], 0, v[80:81]
	global_load_dwordx4 v[6:9], v[2:3], off offset:2048
	s_nop 0
	global_load_dwordx4 v[2:5], v[2:3], off offset:2304
